# P2 rebalanced: 3-tile GEMM workgroups post the internal barrier before their K/V tile (split arrive/wait), SWA units moved to the 2-tile GEMM workgroups (4 each), kn_items moved after the P2-P3 grid b
# speedup vs baseline: 1.0036x; 1.0036x over previous
; #define PG8_STAGE(bufoff, gbase, voff) do { _Pragma("unroll") for (int _i = 0; _i < 2; ++_i) \
;         __builtin_amdgcn_global_load_lds((const unsigned*)((const char*)(gbase) + (voff)[_i]), (LAS unsigned*)(lds + (bufoff) + ldsw + _i * 8192), 16, 0, 0); } while (0)
; #define PG8_WAIT_V(n) asm volatile("s_waitcnt vmcnt(" #n ")" ::: "memory")
; #define PG8_BAR __builtin_amdgcn_s_barrier()
; template <class Epi, bool ALIGN_EPI, bool SP2>
; __device__ __forceinline__ void gemm_phase(LAS unsigned char* lds, const int K, const Sched& S, const Epi& E) {
;     ...
;         PG8_STAGE(PG8_SB(0, 0), cB, voffB); PG8_STAGE(PG8_SB(0, 1), cB + hstep, voffB); PG8_STAGE(PG8_SA(0, 0), cA, voffA); PG8_STAGE(PG8_SA(0, 1), cA + hstep, voffA);
;         if (wr == 1) PG8_BAR;
;         PG8_WAIT_V(2); PG8_BAR;
;         PG8_STAGE(PG8_SB(1, 0), cB + kstep, voffB); PG8_STAGE(PG8_SA(1, 0), cA + kstep, voffA); PG8_STAGE(PG8_SB(1, 1), cB + hstep + kstep, voffB);
;         PG8_WAIT_V(6); PG8_BAR;
;     } else {
;         PG8_STAGE(PG8_SB(0, 0), cB, voffB); PG8_STAGE(PG8_SA(0, 0), cA, voffA); PG8_STAGE(PG8_SB(0, 1), cB + hstep, voffB); PG8_STAGE(PG8_SA(0, 1), cA + hstep, voffA);
;         if (wr == 1) PG8_BAR;
;         PG8_WAIT_V(4); PG8_BAR;
;         PG8_STAGE(PG8_SB(1, 0), cB + kstep, voffB); PG8_STAGE(PG8_SA(1, 0), cA + kstep, voffA); PG8_STAGE(PG8_SB(1, 1), cB + hstep + kstep, voffB);
;         PG8_WAIT_V(6); PG8_BAR;
; __global__ void __launch_bounds__(512, 2) layer_fwd(Args args) {
;     ...
;                 pg8::Sched S; S.A0 = (const char*)(ws + WS_HN1); S.B0 = (const char*)(ws + WS_WIN); S.A1 = (const char*)(ws + WS_MN); S.B1 = (const char*)(ws + WS_WKV);
;                 S.nM0 = M / 256; S.nN0 = INW / 256 - 8; S.pnoff = 8; S.n0 = S.nM0 * S.nN0; S.n1 = (MM / 256) * 4; S.G = F.G - 64; S.c = F.bid - 64; S.tstep = (size_t)256 * D * 2; S.nrep = 1; S.prep();
;                 pg8::gemm_phase<pg8::EpiP1, true, true>(F.lds, D, S, EP1);
.LBB0_344:
	v_bfe_u32 v210, v228, 4, 2
	s_mov_b64 s[16:17], 0x80
	s_and_b32 s24, s6, 3
	v_and_b32_e32 v209, 15, v228
	v_lshlrev_b32_e32 v12, 4, v210
	v_lshlrev_b32_e32 v14, 2, v228
	s_add_i32 m0, s41, 0x18000
	v_lshl_add_u64 v[6:7], v[6:7], 0, s[16:17]
	s_lshl_b32 s22, s96, 6
	s_waitcnt lgkmcnt(0)
	v_lshl_or_b32 v13, v209, 6, v12
	s_lshl_b32 s6, s96, 13
	v_and_b32_e32 v14, 32, v14
	s_lshl_b32 s23, s24, 5
	s_lshl_b32 s19, s24, 12
	s_waitcnt vmcnt(2)
	s_barrier
	global_load_lds_dwordx4 v[6:7], off
	v_lshl_add_u64 v[4:5], v[4:5], 0, s[16:17]
	s_add_i32 m0, s41, 0x1a000
	s_add_i32 s26, s41, 0x8000
	s_add_i32 s27, s41, 0xa000
	v_bitop3_b32 v13, v13, s6, v14 bitop3:0xde
	global_load_lds_dwordx4 v[4:5], off
	v_lshl_add_u64 v[0:1], v[0:1], 0, s[16:17]
	s_mov_b32 m0, s26
	s_add_u32 s6, s70, 0x40080
	global_load_lds_dwordx4 v[0:1], off
	v_lshl_add_u64 v[0:1], v[2:3], 0, s[16:17]
	s_mov_b32 m0, s27
	s_addc_u32 s7, s71, 0
	global_load_lds_dwordx4 v[0:1], off
	s_add_i32 m0, s41, 0x1c000
	v_lshl_add_u64 v[0:1], s[6:7], 0, v[162:163]
	global_load_lds_dwordx4 v[0:1], off
	v_lshl_add_u64 v[0:1], s[6:7], 0, v[166:167]
	s_add_i32 m0, s41, 0x1e000
	s_movk_i32 s6, 0x3c0
	global_load_lds_dwordx4 v[0:1], off
	v_lshlrev_b32_e32 v0, 6, v228
	v_and_or_b32 v0, v0, s6, v12
	v_bitop3_b32 v211, s19, v0, v14 bitop3:0xf6
	v_lshlrev_b32_e32 v0, 8, v228
	v_and_b32_e32 v0, 0x38000, v0
	v_lshlrev_b32_e32 v1, 11, v10
	s_cmpk_lt_u32 s18, 0x100
	v_or3_b32 v0, v8, v0, v1
	s_cselect_b64 s[18:19], -1, 0
	s_cmp_gt_u32 s24, 1
	v_add_u32_e32 v168, v0, v9
	v_lshlrev_b32_e32 v0, 4, v11
	s_cselect_b64 s[52:53], -1, 0
	s_lshl_b32 s6, s24, 6
	s_add_i32 s77, s96, 2
	s_lshl_b32 s7, s24, 7
	v_readlane_b32 s24, v254, 51
	v_and_b32_e32 v0, 0x78000, v0
	s_waitcnt vmcnt(6)
	v_readlane_b32 s25, v254, 52
	s_add_u32 s78, s24, s7
	v_or3_b32 v0, v8, v0, v1
	s_addc_u32 s79, s25, 0
	v_add_u32_e32 v170, v0, v9
	s_add_i32 s28, 0, 0x10000
	s_add_i32 s29, 0, 0x14000
	s_lshl_b32 s6, s6, 1
	v_mbcnt_lo_u32_b32 v0, -1, 0
	v_mov_b32_e32 v169, v163
	v_mov_b32_e32 v171, v163
	v_add_u32_e32 v212, s28, v211
	v_add_u32_e32 v213, s29, v211
	v_add_u32_e32 v214, 0, v13
	v_writelane_b32 v254, s6, 63
	v_mov_b32_e32 v215, 0x358637bd
	s_mov_b64 s[24:25], 0x8000
	s_mov_b64 s[56:57], 0x4000
	s_mov_b64 s[60:61], 0xc000
	s_mov_b64 s[64:65], 0x20000
	s_mov_b64 s[66:67], 0x24000
	s_mov_b64 s[36:37], 0x28000
	s_mov_b64 s[38:39], 0x2c000
	s_mov_b32 s30, 0xc1f00000
	v_mov_b32_e32 v216, 0x3e38aa3b
	v_mbcnt_hi_u32_b32 v217, -1, v0
	v_mov_b32_e32 v218, 0x41f00000
	s_mov_b32 s31, 0
	s_mov_b32 s98, 0
	s_barrier
	s_branch .LBB0_347

; __device__ __forceinline__ unsigned xb_add(unsigned* p, unsigned v) { return __hip_atomic_fetch_add(p, v, __ATOMIC_RELAXED, __HIP_MEMORY_SCOPE_AGENT); }
; template <class Epi, bool ALIGN_EPI, bool SP2>
; __device__ __forceinline__ void gemm_phase(LAS unsigned char* lds, const int K, const Sched& S, const Epi& E) {
;     ...
;     for (;;) {
;         const bool has_next = S.next(ui + 1, nxt);
; __device__ __forceinline__ void xcd_barrier_arrive(const XcdBarrier& b) {
;     asm volatile("s_waitcnt vmcnt(0)" ::: "memory");
;     __syncthreads();
;     if (threadIdx.x == 0) {
;         unsigned* bar = b.bar;
;         __builtin_amdgcn_s_waitcnt(0);
;         unsigned nloc = b.st[0], nx = b.st[1];
;         if (nloc == 0u) { xcd_barrier_complete(bar, b.x, nloc, nx); b.st[0] = nloc; b.st[1] = nx; }
;         const unsigned old = xb_add(&bar[XB_XSUB(b.x)], 1u);
;         const unsigned gen = old / nloc;
;         if (old + 1u == (gen + 1u) * nloc) {
.LBB0_347:
	s_add_i32 s31, s31, 1
	s_cmp_eq_u32 s31, 3
	s_cbranch_scc0 .Larv_skip
	s_cmpk_eq_i32 s33, 0x100
	s_cbranch_scc0 .Larv_skip
	v_writelane_b32 v255, s4, 16
	v_writelane_b32 v255, s5, 17
	v_writelane_b32 v255, s6, 18
	v_writelane_b32 v255, s7, 19
	v_writelane_b32 v255, s8, 20
	v_writelane_b32 v255, s9, 21
	v_writelane_b32 v255, s10, 22
	v_writelane_b32 v255, s11, 23
	v_writelane_b32 v255, s12, 24
	v_writelane_b32 v255, s13, 25
	v_writelane_b32 v255, s14, 26
	v_writelane_b32 v255, s15, 27
	v_writelane_b32 v255, s16, 28
	v_writelane_b32 v255, s17, 29
	v_writelane_b32 v255, s18, 30
	v_writelane_b32 v255, s19, 31
	v_writelane_b32 v255, s20, 32
	v_writelane_b32 v255, s21, 33
	v_writelane_b32 v255, s22, 34
	v_writelane_b32 v255, s23, 35
	v_writelane_b32 v255, s24, 36
	v_writelane_b32 v255, s25, 37
	v_writelane_b32 v255, s26, 38
	v_writelane_b32 v255, s27, 39
	v_writelane_b32 v255, s28, 40
	v_writelane_b32 v255, s85, 41
	v_writelane_b32 v255, s86, 42
	v_writelane_b32 v255, s87, 43
	v_writelane_b32 v255, s94, 44
	v_writelane_b32 v255, s95, 45
	s_mov_b32 s85, s76
	v_readlane_b32 s86, v254, 43
	v_readlane_b32 s87, v254, 44
	v_readlane_b32 s94, v254, 61
	v_readlane_b32 s95, v254, 62
	s_waitcnt vmcnt(0)
	s_waitcnt vmcnt(0) lgkmcnt(0)
	s_barrier
	s_barrier
	s_and_saveexec_b64 s[4:5], s[86:87]
	s_cbranch_execz .Larv_523
	s_add_i32 s6, 0, 0x25020
	v_mov_b32_e32 v0, s6
	s_waitcnt vmcnt(0) expcnt(0) lgkmcnt(0)
	ds_read_b32 v1, v0
	s_add_i32 s6, 0, 0x25024
	v_mov_b32_e32 v0, s6
	ds_read_b32 v0, v0
	s_waitcnt lgkmcnt(1)
	v_cmp_ne_u32_e32 vcc, 0, v1

; __device__ __forceinline__ unsigned xb_ld(unsigned* p)              { return __hip_atomic_load(p, __ATOMIC_RELAXED, __HIP_MEMORY_SCOPE_AGENT); }
; __device__ __forceinline__ unsigned xb_add(unsigned* p, unsigned v) { return __hip_atomic_fetch_add(p, v, __ATOMIC_RELAXED, __HIP_MEMORY_SCOPE_AGENT); }
; #define XB_SPIN(cond, bar) do { unsigned _sp = 0; while (cond) { __builtin_amdgcn_s_sleep(1); \
;     if ((++_sp & 255u) == 0u) { if (xb_ld(&(bar)[XB_TMO])) break; if (_sp > XB_SPIN_CAP) { atomicAdd(&(bar)[XB_TMO], 1u); break; } } } } while (0)
;     __device__ __forceinline__ bool next(int i, Unit& u) const {
;         int L = i * G + c;
;         if (nrep > 1) { if (L < n0 * nrep) { const int pass = L / n0; tile(L - pass * n0, u.pm, u.pn); u.kind = (pass + 1 < nrep) ? 2 : 0; return true; } L -= n0 * (nrep - 1); }
;         if (L < n0) { tile(L, u.pm, u.pn); u.pn += pnoff; u.kind = 0; return true; }
;         if (L < n0 + n1) { const int idx = L - n0; u.pm = idx >> 2; u.pn = idx & 3; u.kind = 1; return true; }
;         return false;
; __device__ __forceinline__ void xcd_barrier_arrive(const XcdBarrier& b) {
;     ...
;             __builtin_amdgcn_fence(__ATOMIC_RELEASE, "agent");
;             asm volatile("s_waitcnt vmcnt(0)" ::: "memory");
;             const unsigned og = xb_add(&bar[XB_TOP], 1u);
;             const unsigned tg = og / nx;
;             if (og + 1u == (tg + 1u) * nx) xb_add(&bar[XB_TOPGEN], 1u);
;             else XB_SPIN(xb_ld(&bar[XB_TOPGEN]) == tg, bar);
;             xb_add(&bar[XB_XGEN(b.x)], 1u);
;             asm volatile("s_waitcnt vmcnt(0)" ::: "memory");
;             b.st[5] = 1u;
;         } else b.st[5] = 0u;
;         b.st[4] = gen;
;     }
; }
.Larv_523:
	s_or_b64 exec, exec, s[4:5]
	s_waitcnt vmcnt(0) lgkmcnt(0)
	v_readlane_b32 s4, v255, 16
	v_readlane_b32 s5, v255, 17
	v_readlane_b32 s6, v255, 18
	v_readlane_b32 s7, v255, 19
	v_readlane_b32 s8, v255, 20
	v_readlane_b32 s9, v255, 21
	v_readlane_b32 s10, v255, 22
	v_readlane_b32 s11, v255, 23
	v_readlane_b32 s12, v255, 24
	v_readlane_b32 s13, v255, 25
	v_readlane_b32 s14, v255, 26
	v_readlane_b32 s15, v255, 27
	v_readlane_b32 s16, v255, 28
	v_readlane_b32 s17, v255, 29
	v_readlane_b32 s18, v255, 30
	v_readlane_b32 s19, v255, 31
	v_readlane_b32 s20, v255, 32
	v_readlane_b32 s21, v255, 33
	v_readlane_b32 s22, v255, 34
	v_readlane_b32 s23, v255, 35
	v_readlane_b32 s24, v255, 36
	v_readlane_b32 s25, v255, 37
	v_readlane_b32 s26, v255, 38
	v_readlane_b32 s27, v255, 39
	v_readlane_b32 s28, v255, 40
	v_readlane_b32 s85, v255, 41
	v_readlane_b32 s86, v255, 42
	v_readlane_b32 s87, v255, 43
	v_readlane_b32 s94, v255, 44
	v_readlane_b32 s95, v255, 45
	s_mov_b32 s98, 1
.Larv_skip:
	s_mul_i32 s35, s31, s69
	s_add_i32 s35, s35, s68
	s_cmpk_gt_i32 s35, 0x17f
	s_mov_b64 s[6:7], -1
	s_cbranch_scc0 .LBB0_350
	s_mov_b64 s[6:7], 0
	s_cmpk_gt_u32 s35, 0x1bf
	s_mov_b64 s[46:47], 0
	s_cbranch_scc1 .LBB0_350
	s_add_i32 s34, s35, 0xfffffe80
	s_and_b32 s44, s35, 3
	s_lshr_b32 s42, s34, 2
	s_mov_b32 s34, 1
	s_mov_b64 s[46:47], -1

; __device__ __forceinline__ unsigned xb_ld(unsigned* p)              { return __hip_atomic_load(p, __ATOMIC_RELAXED, __HIP_MEMORY_SCOPE_AGENT); }
; __device__ __forceinline__ void xcd_barrier_complete(unsigned* bar, unsigned x, unsigned& nloc, unsigned& nx) {
;     const unsigned G = gridDim.x * gridDim.y * gridDim.z;
;     unsigned sum, cnt, mine, sp = 0u;
;     for (;;) {
;         sum = 0u; cnt = 0u; mine = 0u;
; #pragma unroll
;         for (unsigned j = 0; j < 16; ++j) { const unsigned c = xb_ld(&bar[XB_XCNT(j)]); sum += c; cnt += (c > 0u) ? 1u : 0u; mine = (j == x) ? c : mine; }
;         if (sum == G) break;
;         __builtin_amdgcn_s_sleep(1);
;         if ((++sp & 255u) == 0u) { if (xb_ld(&bar[XB_TMO])) break; if (sp > XB_SPIN_CAP) { atomicAdd(&bar[XB_TMO], 1u); break; } }
;     }
; __device__ __forceinline__ void xcd_barrier(const XcdBarrier& b) {
;     asm volatile("s_waitcnt vmcnt(0)" ::: "memory");
;     __syncthreads();
;     if (threadIdx.x == 0) {
;         unsigned* bar = b.bar;
;         __builtin_amdgcn_s_waitcnt(0);
;         unsigned nloc = b.st[0], nx = b.st[1];
;         if (nloc == 0u) { xcd_barrier_complete(bar, b.x, nloc, nx); b.st[0] = nloc; b.st[1] = nx; }
.LBB0_430:
	s_cmp_eq_u32 s98, 1
	s_cbranch_scc1 .LBB0_566
	s_waitcnt vmcnt(0)
	s_barrier
	s_and_saveexec_b64 s[4:5], s[86:87]
	s_cbranch_execz .LBB0_482
	s_add_i32 s6, 0, 0x25020
	v_mov_b32_e32 v0, s6
	s_waitcnt vmcnt(0) expcnt(0) lgkmcnt(0)
	ds_read_b32 v2, v0
	s_add_i32 s6, 0, 0x25024
	v_mov_b32_e32 v0, s6
	ds_read_b32 v0, v0
	s_waitcnt lgkmcnt(1)
	v_cmp_ne_u32_e32 vcc, 0, v2
	s_cbranch_vccnz .LBB0_446
	s_add_u32 s6, s92, 0x4200
	s_addc_u32 s7, s93, 0
	s_add_u32 s8, s92, 0x4400
	s_addc_u32 s9, s93, 0
	s_add_u32 s10, s92, 0x4500
	s_addc_u32 s11, s93, 0
	s_add_u32 s12, s92, 0x4600
	s_addc_u32 s13, s93, 0
	s_add_u32 s14, s92, 0x4700
	s_addc_u32 s15, s93, 0
	s_add_u32 s16, s92, 0x4800
	s_addc_u32 s17, s93, 0
	s_add_u32 s18, s92, 0x4900
	s_addc_u32 s19, s93, 0
	s_add_u32 s20, s92, 0x4a00
	s_addc_u32 s21, s93, 0
	s_add_u32 s22, s92, 0x4b00
	s_addc_u32 s23, s93, 0
	s_add_u32 s24, s92, 0x4c00
	s_addc_u32 s25, s93, 0
	s_add_u32 s26, s92, 0x4d00
	s_addc_u32 s27, s93, 0
	s_add_u32 s28, s92, 0x4e00
	s_addc_u32 s29, s93, 0
	s_add_u32 s30, s92, 0x4f00
	s_addc_u32 s31, s93, 0
	s_add_u32 s34, s92, 0x5000
	s_addc_u32 s35, s93, 0
	s_add_u32 s36, s92, 0x5100
	s_addc_u32 s37, s93, 0
	s_add_u32 s38, s92, 0x5200
	s_addc_u32 s39, s93, 0
	s_mul_i32 s48, s97, s33
	s_add_u32 s40, s92, 0x5300
	s_mul_i32 s48, s48, s96
	s_addc_u32 s41, s93, 0
	s_mov_b32 s49, 1
	v_mov_b32_e32 v16, 0
	s_branch .LBB0_434

; #define LAS __attribute__((address_space(3)))
; __device__ __forceinline__ void swa_load(Frame& F, int u, u32x4 (&kt_)[4], u32x4 (&vt_)[4]) {
;     const bf16_t* SK = (const bf16_t*)(F.ws + WS_SK); const bf16_t* SV = (const bf16_t*)(F.ws + WS_SV);
;     const int b = u >> 5, n = (u >> 1) & 15, kvh = u & 1, lane = F.lane;
; #pragma unroll
;     for (int it = 0; it < 4; ++it) { const int i = F.wave * 64 + lane + 512 * it, key = i >> 3, ch = i & 7;
;         const int keyl = (n > 0 || key >= 128) ? key : key + 128; const size_t row = (size_t)b * SEQ + (n - 1) * 128 + keyl;
;         kt_[it] = *(const u32x4*)(SK + row * 128 + kvh * 64 + 8 * ch); vt_[it] = *(const u32x4*)(SV + row * 128 + kvh * 64 + 8 * ch); }
; }
; __device__ __forceinline__ void swa_stage(Frame& F, const u32x4 (&kt_)[4], const u32x4 (&vt_)[4]) {
;     LAS unsigned char* Kimg = F.lds; LAS unsigned char* Vimg = F.lds + 32768; const int lane = F.lane;
; #pragma unroll
;     for (int it = 0; it < 4; ++it) { const int i = F.wave * 64 + lane + 512 * it, key = i >> 3, ch = i & 7;
;         *(LAS u32x4*)(Kimg + offa<1024>(key, ch)) = kt_[it]; *(LAS u32x4*)(Vimg + offa<1024>(key, ch)) = vt_[it]; }
; }
; __device__ __forceinline__ void swa_units(Frame& F, int u0, int stride) {
;     if (u0 >= 512) return;
;     u32x4 kt_[4], vt_[4];
;     __syncthreads();
;     swa_load(F, u0, kt_, vt_);
;     swa_stage(F, kt_, vt_);
;     __syncthreads();
.LBB0_583:
	s_mov_b32 s101, s2
	s_mov_b32 s100, s33
	s_movk_i32 s99, 0x200
	s_cmpk_eq_i32 s33, 0x100
	s_cbranch_scc0 .Lswa_cfg
	s_movk_i32 s100, 0x80
	s_movk_i32 s101, 0x200
	s_cmp_gt_i32 s2, 0x7f
	s_cbranch_scc0 .Lswa_cfg
	s_add_i32 s101, s2, 0xffffff80
.Lswa_cfg:
	v_readlane_b32 s0, v254, 53
	s_cmp_ge_i32 s101, s99
	v_readlane_b32 s1, v254, 54
	s_waitcnt lgkmcnt(0)
	s_cbranch_scc1 .LBB0_608
	s_ashr_i32 s4, s101, 5
	s_bfe_u32 s6, s101, 0x40001
	s_cmp_lg_u32 s6, 0
	s_cselect_b64 s[10:11], -1, 0
	s_lshl_b32 s6, s6, 7
	s_ashr_i32 s5, s4, 31
	s_addk_i32 s6, 0xff80
	s_lshl_b64 s[4:5], s[4:5], 11
	s_ashr_i32 s7, s6, 31
	s_add_u32 s12, s4, s6
	s_addc_u32 s13, s5, s7
	s_lshl_b32 s4, s101, 7
	s_lshl_b32 s48, s101, 6
	s_and_b32 s6, s4, 0x80
	v_readlane_b32 s16, v254, 49
	v_readlane_b32 s17, v254, 50
	s_add_u32 s4, s16, s6
	v_lshlrev_b32_e32 v0, 4, v228
	s_addc_u32 s5, s17, 0
	v_and_b32_e32 v0, 0x70, v0
	v_mov_b32_e32 v1, 0
	v_readlane_b32 s18, v254, 51
	v_lshl_add_u64 v[2:3], s[4:5], 0, v[0:1]
	v_readlane_b32 s19, v254, 52
	s_add_u32 s4, s18, s6
	s_addc_u32 s5, s19, 0
	v_readlane_b32 s14, v254, 42
	v_lshl_add_u64 v[4:5], s[4:5], 0, v[0:1]
	s_and_b32 s4, s14, 0xffffffc0
	v_or_b32_e32 v10, s4, v208
	v_ashrrev_i32_e32 v154, 3, v10
	s_movk_i32 s8, 0x7f
	v_cmp_lt_i32_e64 s[46:47], s8, v154
	v_add_u32_e32 v155, 0x80, v154
	s_or_b64 vcc, s[10:11], s[46:47]
	v_cndmask_b32_e32 v6, v155, v154, vcc
	v_ashrrev_i32_e32 v7, 31, v6
	v_lshl_add_u64 v[6:7], s[12:13], 0, v[6:7]
	v_lshlrev_b64 v[6:7], 8, v[6:7]
	v_lshl_add_u64 v[8:9], v[2:3], 0, v[6:7]
	v_lshl_add_u64 v[6:7], v[4:5], 0, v[6:7]
	s_waitcnt vmcnt(0)
	s_barrier
	global_load_dwordx4 v[96:99], v[8:9], off
	global_load_dwordx4 v[100:103], v[6:7], off
	v_add_u32_e32 v6, 0x200, v10
	v_ashrrev_i32_e32 v156, 3, v6
	v_cmp_lt_i32_e64 s[4:5], s8, v156
	v_add_u32_e32 v157, 0x80, v156
	s_or_b64 vcc, s[10:11], s[4:5]
	v_cndmask_b32_e32 v6, v157, v156, vcc
	v_ashrrev_i32_e32 v7, 31, v6
	v_lshl_add_u64 v[6:7], s[12:13], 0, v[6:7]
	v_lshlrev_b64 v[6:7], 8, v[6:7]
	v_lshl_add_u64 v[8:9], v[2:3], 0, v[6:7]
	v_lshl_add_u64 v[6:7], v[4:5], 0, v[6:7]
	global_load_dwordx4 v[104:107], v[8:9], off
	global_load_dwordx4 v[108:111], v[6:7], off
	v_add_u32_e32 v6, 0x400, v10
	v_ashrrev_i32_e32 v158, 3, v6
	v_cmp_lt_i32_e64 s[6:7], s8, v158
	v_add_u32_e32 v159, 0x80, v158
	s_or_b64 vcc, s[10:11], s[6:7]
	v_cndmask_b32_e32 v6, v159, v158, vcc
	v_ashrrev_i32_e32 v7, 31, v6
	v_lshl_add_u64 v[6:7], s[12:13], 0, v[6:7]
	v_lshlrev_b64 v[6:7], 8, v[6:7]
	v_lshl_add_u64 v[8:9], v[2:3], 0, v[6:7]
	v_lshl_add_u64 v[6:7], v[4:5], 0, v[6:7]
	global_load_dwordx4 v[112:115], v[8:9], off
	global_load_dwordx4 v[116:119], v[6:7], off
	v_add_u32_e32 v6, 0x600, v10
	v_ashrrev_i32_e32 v160, 3, v6
	v_cmp_lt_i32_e64 s[8:9], s8, v160
	v_add_u32_e32 v161, 0x80, v160
	s_or_b64 vcc, s[10:11], s[8:9]
	v_cndmask_b32_e32 v6, v161, v160, vcc
	v_ashrrev_i32_e32 v7, 31, v6
	v_lshl_add_u64 v[6:7], s[12:13], 0, v[6:7]
	v_lshlrev_b64 v[6:7], 8, v[6:7]
	v_lshl_add_u64 v[2:3], v[2:3], 0, v[6:7]
	v_lshl_add_u64 v[4:5], v[4:5], 0, v[6:7]
	global_load_dwordx4 v[120:123], v[2:3], off
	global_load_dwordx4 v[124:127], v[4:5], off
	v_lshrrev_b32_e32 v5, 2, v154
	v_lshlrev_b32_e32 v4, 6, v154
	v_xor_b32_e32 v5, v5, v228
	v_lshlrev_b32_e32 v2, 7, v228
	s_movk_i32 s10, 0xfc00
	v_lshlrev_b32_e32 v3, 7, v154
	v_and_b32_e32 v4, 0x1c0, v4
	v_lshlrev_b32_e32 v5, 4, v5
	v_and_b32_e32 v2, 0x200, v2
	v_lshlrev_b32_e32 v7, 6, v156
	v_lshrrev_b32_e32 v8, 2, v156
	v_and_or_b32 v3, v3, s10, v4
	v_and_b32_e32 v5, 48, v5
	v_and_b32_e32 v4, 0x1c0, v7
	v_xor_b32_e32 v7, v8, v228
	v_or3_b32 v3, v3, v5, v2
	v_lshlrev_b32_e32 v6, 7, v156
	v_add_u32_e32 v162, 0, v3
	v_lshlrev_b32_e32 v3, 4, v7
	v_and_b32_e32 v3, 48, v3
	v_and_or_b32 v4, v6, s10, v4
	v_lshrrev_b32_e32 v5, 2, v158
	v_or3_b32 v3, v4, v3, v2
	v_lshlrev_b32_e32 v4, 6, v158
	v_xor_b32_e32 v5, v5, v228
	v_add_u32_e32 v163, 0, v3
	v_lshlrev_b32_e32 v3, 7, v158
	v_and_b32_e32 v4, 0x1c0, v4
	v_lshlrev_b32_e32 v5, 4, v5
	v_and_b32_e32 v5, 48, v5
	v_and_or_b32 v3, v3, s10, v4
	v_or3_b32 v3, v3, v5, v2
	v_lshlrev_b32_e32 v4, 6, v160
	v_add_u32_e32 v164, 0, v3
	v_lshlrev_b32_e32 v3, 7, v160
	v_and_b32_e32 v4, 0x1c0, v4
	v_lshrrev_b32_e32 v5, 2, v160
	v_xor_b32_e32 v5, v5, v228
	v_and_or_b32 v3, v3, s10, v4
	s_mul_i32 s10, s3, 0x1200
	v_lshlrev_b32_e32 v5, 4, v5
	s_add_i32 s49, s10, 0
	s_lshl_b32 s10, s3, 1
	v_and_b32_e32 v5, 48, v5
	s_and_b32 s51, s10, 2
	v_or3_b32 v2, v3, v5, v2
	v_lshl_add_u64 v[144:145], s[16:17], 0, v[0:1]
	v_lshl_add_u64 v[146:147], s[18:19], 0, v[0:1]
	s_lshl_b32 s57, s51, 12
	s_or_b32 s10, s51, 1
	v_mbcnt_lo_u32_b32 v0, -1, 0
	s_mov_b32 s53, 0
	v_add_u32_e32 v165, 0, v2
	s_add_i32 s49, s49, 0x10000
	s_lshr_b32 s50, s14, 7
	s_lshl_b32 s56, s51, 5
	s_or_b32 s62, s57, 0x4000
	s_lshl_b32 s63, s10, 5
	s_lshl_b32 s64, s10, 12
	s_lshl_b32 s65, s100, 6
	s_lshl_b32 s66, s101, 2
	s_lshl_b32 s67, s100, 2
	v_mbcnt_hi_u32_b32 v166, -1, v0
	s_movk_i32 s68, 0x90
	s_mov_b32 s69, 0xb000000
	s_mov_b32 s10, s101
	s_waitcnt vmcnt(7)
	ds_write_b128 v162, v[96:99]
	s_waitcnt vmcnt(6)
	ds_write_b128 v162, v[100:103] offset:32768
	s_waitcnt vmcnt(5)
	ds_write_b128 v163, v[104:107]
	s_waitcnt vmcnt(4)
	ds_write_b128 v163, v[108:111] offset:32768
	s_waitcnt vmcnt(3)
	ds_write_b128 v164, v[112:115]
	s_waitcnt vmcnt(2)
	ds_write_b128 v164, v[116:119] offset:32768
	s_waitcnt vmcnt(1)
	ds_write_b128 v165, v[120:123]
	s_waitcnt vmcnt(0)
	ds_write_b128 v165, v[124:127] offset:32768
	s_waitcnt lgkmcnt(0)
	s_barrier
	s_branch .LBB0_586

; __device__ __forceinline__ void swa_load(Frame& F, int u, u32x4 (&kt_)[4], u32x4 (&vt_)[4]) {
;     const bf16_t* SK = (const bf16_t*)(F.ws + WS_SK); const bf16_t* SV = (const bf16_t*)(F.ws + WS_SV);
;     const int b = u >> 5, n = (u >> 1) & 15, kvh = u & 1, lane = F.lane;
; #pragma unroll
;     for (int it = 0; it < 4; ++it) { const int i = F.wave * 64 + lane + 512 * it, key = i >> 3, ch = i & 7;
;         const int keyl = (n > 0 || key >= 128) ? key : key + 128; const size_t row = (size_t)b * SEQ + (n - 1) * 128 + keyl;
;         kt_[it] = *(const u32x4*)(SK + row * 128 + kvh * 64 + 8 * ch); vt_[it] = *(const u32x4*)(SV + row * 128 + kvh * 64 + 8 * ch); }
; }
; __device__ __forceinline__ void swa_units(Frame& F, int u0, int stride) {
;     ...
;     for (int u = u0;;) {
;         const int un = u + stride; const bool has = un < 512;
;         if (has) swa_load(F, un, kt_, vt_);
.LBB0_586:
	s_add_i32 s70, s10, s100
	s_cmp_lt_i32 s70, s99
	s_cselect_b64 s[54:55], -1, 0
	s_cmp_ge_i32 s70, s99
	s_cbranch_scc1 .LBB0_588
	s_ashr_i32 s12, s70, 5
	s_bfe_u32 s11, s70, 0x40001
	s_cmp_lg_u32 s11, 0
	s_cselect_b64 s[14:15], -1, 0
	s_lshl_b32 s11, s11, 7
	s_ashr_i32 s13, s12, 31
	s_addk_i32 s11, 0xff80
	s_lshl_b64 s[12:13], s[12:13], 11
	s_ashr_i32 s16, s11, 31
	s_add_u32 s12, s12, s11
	s_addc_u32 s13, s13, s16
	s_or_b64 vcc, s[46:47], s[14:15]
	s_add_i32 s11, s65, s48
	v_cndmask_b32_e32 v6, v155, v154, vcc
	s_and_b32 s11, s11, 64
	v_ashrrev_i32_e32 v7, 31, v6
	s_lshl_b32 s52, s11, 1
	v_lshl_add_u64 v[6:7], s[12:13], 0, v[6:7]
	v_lshl_add_u64 v[2:3], v[144:145], 0, s[52:53]
	v_lshl_add_u64 v[4:5], v[146:147], 0, s[52:53]
	v_lshlrev_b64 v[6:7], 8, v[6:7]
	v_lshl_add_u64 v[8:9], v[2:3], 0, v[6:7]
	v_lshl_add_u64 v[6:7], v[4:5], 0, v[6:7]
	s_or_b64 vcc, s[4:5], s[14:15]
	global_load_dwordx4 v[96:99], v[8:9], off
	global_load_dwordx4 v[100:103], v[6:7], off
	v_cndmask_b32_e32 v6, v157, v156, vcc
	v_ashrrev_i32_e32 v7, 31, v6
	v_lshl_add_u64 v[6:7], s[12:13], 0, v[6:7]
	v_lshlrev_b64 v[6:7], 8, v[6:7]
	v_lshl_add_u64 v[8:9], v[2:3], 0, v[6:7]
	v_lshl_add_u64 v[6:7], v[4:5], 0, v[6:7]
	s_or_b64 vcc, s[6:7], s[14:15]
	global_load_dwordx4 v[104:107], v[8:9], off
	global_load_dwordx4 v[108:111], v[6:7], off
	v_cndmask_b32_e32 v6, v159, v158, vcc
	v_ashrrev_i32_e32 v7, 31, v6
	v_lshl_add_u64 v[6:7], s[12:13], 0, v[6:7]
	v_lshlrev_b64 v[6:7], 8, v[6:7]
	v_lshl_add_u64 v[8:9], v[2:3], 0, v[6:7]
	v_lshl_add_u64 v[6:7], v[4:5], 0, v[6:7]
	s_or_b64 vcc, s[8:9], s[14:15]
	global_load_dwordx4 v[112:115], v[8:9], off
	global_load_dwordx4 v[116:119], v[6:7], off
	v_cndmask_b32_e32 v6, v161, v160, vcc
	v_ashrrev_i32_e32 v7, 31, v6
	v_lshl_add_u64 v[6:7], s[12:13], 0, v[6:7]
	v_lshlrev_b64 v[6:7], 8, v[6:7]
	v_lshl_add_u64 v[2:3], v[2:3], 0, v[6:7]
	v_lshl_add_u64 v[4:5], v[4:5], 0, v[6:7]
	global_load_dwordx4 v[120:123], v[2:3], off
	global_load_dwordx4 v[124:127], v[4:5], off

; __global__ void __launch_bounds__(512, 2) layer_fwd(Args args) {
;     ...
;             swa_units(F, F.bid, F.G);
;             __syncthreads();
;             if (F.bid >= 64) kn_items(F, (F.bid - 64) * 8 + F.wave, (F.G - 64) * 8);
.LBB0_607:
	s_branch .LBB0_601
.LBB0_608:
	s_waitcnt vmcnt(0)
	s_barrier
.LBB0_624:
	v_readlane_b32 s4, v255, 0
	v_readlane_b32 s5, v255, 1

; __device__ __forceinline__ void kn_items(Frame& F, int it0, int stride) {
;     const bf16_t* KVM = (const bf16_t*)(F.ws + WS_KVM); bf16_t* KN = (bf16_t*)(F.ws + WS_KN);
;     const int lane = F.lane; const float g0 = F.xkg[2 * lane], g1 = F.xkg[2 * lane + 1];
;     for (int it = it0; it < MM * 4; it += 4 * stride) {
;         unsigned w[4];
; #pragma unroll
;         for (int j = 0; j < 4; ++j) { const int item = it + j * stride; w[j] = (item < MM * 4) ? *(const unsigned*)(KVM + (size_t)(item >> 2) * 1024 + (item & 3) * 128 + 2 * lane) : 0u; }
;         __builtin_amdgcn_sched_barrier(0);
; __global__ void __launch_bounds__(512, 2) layer_fwd(Args args) {
;     ...
;             if (F.bid >= 64) kn_items(F, (F.bid - 64) * 8 + F.wave, (F.G - 64) * 8);
.LBB0_679:
	s_cmp_lt_i32 s2, 64
	s_cbranch_scc1 .Lkn_done
	v_writelane_b32 v255, s4, 16
	v_writelane_b32 v255, s5, 17
	v_writelane_b32 v255, s6, 18
	v_writelane_b32 v255, s7, 19
	v_writelane_b32 v255, s8, 20
	v_writelane_b32 v255, s9, 21
	v_writelane_b32 v255, s10, 22
	v_writelane_b32 v255, s11, 23
	v_writelane_b32 v255, s12, 24
	v_writelane_b32 v255, s13, 25
	v_writelane_b32 v255, s14, 26
	v_writelane_b32 v255, s15, 27
	v_writelane_b32 v255, s16, 28
	v_writelane_b32 v255, s17, 29
	v_writelane_b32 v255, s18, 30
	v_writelane_b32 v255, s19, 31
	v_writelane_b32 v255, s20, 32
	v_writelane_b32 v255, s21, 33
	v_writelane_b32 v255, s22, 34
	v_writelane_b32 v255, s23, 35
	v_writelane_b32 v255, s24, 36
	v_writelane_b32 v255, s25, 37
	v_writelane_b32 v255, s26, 38
	v_writelane_b32 v255, s27, 39
	v_writelane_b32 v255, s28, 40
	v_writelane_b32 v255, s29, 41
	v_mov_b32_e32 v250, v2
	v_mov_b32_e32 v251, v3
	v_readlane_b32 s0, v254, 53
	v_readlane_b32 s1, v254, 54
	s_lshl_b32 s4, s2, 3
	s_add_i32 s12, s4, s3
	s_add_i32 s4, s12, 0xfffffe00
	s_cmpk_gt_i32 s4, 0x3fff
	s_cbranch_scc1 .Lkn_end
	v_readlane_b32 s16, v254, 0
	v_lshlrev_b32_e32 v0, 3, v208
	v_readlane_b32 s17, v254, 1
	v_mbcnt_lo_u32_b32 v3, -1, 0
	v_mbcnt_hi_u32_b32 v3, -1, v3
	v_and_b32_e32 v4, 64, v3
	v_add_u32_e32 v9, 64, v4
	v_xor_b32_e32 v4, 1, v3
	global_load_dwordx2 v[0:1], v0, s[16:17]
	v_cmp_lt_i32_e32 vcc, v4, v9
	v_xor_b32_e32 v5, 2, v3
	v_xor_b32_e32 v6, 4, v3
	v_cndmask_b32_e32 v4, v3, v4, vcc
	v_cmp_lt_i32_e32 vcc, v5, v9
	v_xor_b32_e32 v7, 8, v3
	v_readlane_b32 s18, v254, 2
	v_cndmask_b32_e32 v5, v3, v5, vcc
	v_cmp_lt_i32_e32 vcc, v6, v9
	v_xor_b32_e32 v8, 16, v3
	s_lshl_b32 s18, s33, 3
	v_cndmask_b32_e32 v6, v3, v6, vcc
	v_cmp_lt_i32_e32 vcc, v7, v9
	v_xor_b32_e32 v10, 32, v3
	v_readlane_b32 s20, v254, 4
	v_cndmask_b32_e32 v7, v3, v7, vcc
	v_cmp_lt_i32_e32 vcc, v8, v9
	s_add_u32 s13, s92, 0x2a00000
	v_readlane_b32 s19, v254, 3
	v_cndmask_b32_e32 v8, v3, v8, vcc
	v_cmp_lt_i32_e32 vcc, v10, v9
	v_readlane_b32 s21, v254, 5
	v_readlane_b32 s22, v254, 6
	v_readlane_b32 s23, v254, 7
	s_addc_u32 s14, s93, 0
	v_lshlrev_b32_e32 v2, 1, v208
	v_cndmask_b32_e32 v3, v3, v10, vcc
	s_lshl_b32 s15, s33, 4
	s_lshl_b32 s16, s33, 5
	s_mul_i32 s17, s33, 24
	s_lshl_b32 s20, s33, 12
	v_lshlrev_b32_e32 v4, 2, v4
	v_lshlrev_b32_e32 v5, 2, v5
	v_lshlrev_b32_e32 v6, 2, v6
	v_lshlrev_b32_e32 v7, 2, v7
	v_lshlrev_b32_e32 v8, 2, v8
	v_lshlrev_b32_e32 v9, 2, v3
	s_addk_i32 s15, 0xfa00
	s_addk_i32 s16, 0xf800
	s_addk_i32 s17, 0xf800
	s_addk_i32 s18, 0xfc00
	s_lshl_b32 s19, s4, 7
	s_add_i32 s20, s20, 0xfffc0000
	v_lshlrev_b32_e32 v10, 1, v2
	s_mov_b32 s21, 0xffff0000
	v_mov_b32_e32 v11, 0x358637bd
	s_mov_b32 s22, 0xf800000
	v_mov_b32_e32 v12, 0x260
	s_movk_i32 s23, 0x7fff
	v_mov_b32_e32 v13, 1
	s_branch .Lkn_612

; __device__ __forceinline__ unsigned pk2(float lo, float hi) { return f2bf(lo) | (f2bf(hi) << 16); }
; __device__ __forceinline__ void kn_items(Frame& F, int it0, int stride) {
;     ...
;     for (int it = it0; it < MM * 4; it += 4 * stride) {
;         unsigned w[4];
; #pragma unroll
;         for (int j = 0; j < 4; ++j) { const int item = it + j * stride; w[j] = (item < MM * 4) ? *(const unsigned*)(KVM + (size_t)(item >> 2) * 1024 + (item & 3) * 128 + 2 * lane) : 0u; }
;         __builtin_amdgcn_sched_barrier(0);
; #pragma unroll
;         for (int j = 0; j < 4; ++j) { const int item = it + j * stride; const float a = bflo(w[j]), b = bfhi(w[j]);
;             const float rstd = 1.0f / sqrtf(wave_sum(a * a + b * b) * (1.0f / 128.0f) + EPS);
;             if (item < MM * 4) *(unsigned*)(KN + (size_t)(item >> 2) * 512 + (item & 3) * 128 + 2 * lane) = pk2(a * rstd * g0, b * rstd * g1); }
;     }
.Lkn_end:
	s_waitcnt vmcnt(0) lgkmcnt(0)
	v_readlane_b32 s4, v255, 16
	v_readlane_b32 s5, v255, 17
	v_readlane_b32 s6, v255, 18
	v_readlane_b32 s7, v255, 19
	v_readlane_b32 s8, v255, 20
	v_readlane_b32 s9, v255, 21
	v_readlane_b32 s10, v255, 22
	v_readlane_b32 s11, v255, 23
	v_readlane_b32 s12, v255, 24
	v_readlane_b32 s13, v255, 25
	v_readlane_b32 s14, v255, 26
	v_readlane_b32 s15, v255, 27
	v_readlane_b32 s16, v255, 28
	v_readlane_b32 s17, v255, 29
	v_readlane_b32 s18, v255, 30
	v_readlane_b32 s19, v255, 31
	v_readlane_b32 s20, v255, 32
	v_readlane_b32 s21, v255, 33
	v_readlane_b32 s22, v255, 34
	v_readlane_b32 s23, v255, 35
	v_readlane_b32 s24, v255, 36
	v_readlane_b32 s25, v255, 37
	v_readlane_b32 s26, v255, 38
	v_readlane_b32 s27, v255, 39
	v_readlane_b32 s28, v255, 40
	v_readlane_b32 s29, v255, 41
	v_readlane_b32 s0, v254, 40
	v_readlane_b32 s1, v254, 41
	v_mov_b32_e32 v2, v250
	v_mov_b32_e32 v3, v251
